# combo2 + up-GEMM first K-iteration peeled with SrcC=0 (accumulator zeroing removed for 44 of 62 tiles)
# speedup vs baseline: 1.0118x; 1.0006x over previous
; #define PG8_STAGE(bufoff, gbase, voff) do { _Pragma("unroll") for (int _i = 0; _i < 2; ++_i) \
;         __builtin_amdgcn_global_load_lds((const unsigned*)((const char*)(gbase) + (voff)[_i]), (PG8_LAS unsigned*)(lds + (bufoff) + ldsw + _i * 8192), 16, 0, 0); } while (0)
; #define PG8_LDA(dst, b, h) do { _Pragma("unroll") for (int m = 0; m < 4; ++m) _Pragma("unroll") for (int k = 0; k < 2; ++k) dst[m][k] = *(const PG8_LAS bf16x8*)(lds + PG8_SA(b, h) + aoff + m * 2048 + k * 1024); } while (0)
; #define PG8_LDB(dst, b, h) do { _Pragma("unroll") for (int n = 0; n < 2; ++n) _Pragma("unroll") for (int k = 0; k < 2; ++k) dst[n][k] = *(const PG8_LAS bf16x8*)(lds + PG8_SB(b, h) + boff + n * 2048 + k * 1024); } while (0)
; #define PG8_MMA(ai, bj, At, Bt) do { __builtin_amdgcn_s_setprio(1); _Pragma("unroll") for (int m = 0; m < 4; ++m) _Pragma("unroll") for (int n = 0; n < 2; ++n) _Pragma("unroll") for (int k = 0; k < 2; ++k) \
;         acc[ai][bj][m][n] = __builtin_amdgcn_mfma_f32_16x16x32_bf16(Bt[n][k], At[m][k], acc[ai][bj][m][n], 0, 0, 0); __builtin_amdgcn_s_setprio(0); } while (0)
; template <class Epi, class Sched, bool ALIGN_EPI = false, bool SP2 = false>
; __device__ __forceinline__ void gemm_phase(PG8_LAS unsigned char* lds, const Gemm g, const Sched& S, const Epi& E, const int tid) {
;     ...
;         const char* nA = has_next ? (const char*)g.A + (size_t)nxt.pm * tstep : cA; const char* nB = has_next ? (const char*)g.Bt + (size_t)nxt.pn * tstep : cB;
;         for (int t = 0; t < nt; t += 2) {
;             const bool last = (t == nt - 2);
;             const char* a1 = cA + (size_t)(t + 1) * kstep;
;             const char* a2 = last ? nA : cA + (size_t)(t + 2) * kstep; const char* b2 = last ? nB : cB + (size_t)(t + 2) * kstep;
;             const char* a3 = a2 + kstep; const char* b3 = b2 + kstep;
;             if (last && has_next) S.a_ready(nxt);
;             if (last) E.prefetch(lds + EPI_LDS_OFF + wid * 1024, cur, wr, wc, lane);
;             if constexpr (SP2) {
;             PG8_LDB(B0, 0, 0); PG8_LDB(B1, 0, 1); PG8_SCHED; PG8_LDA(At, 0, 0); PG8_STAGE(PG8_SA(1, 1), a1 + hstep, voffA);
;             PG8_WAIT_V(8); PG8_WAIT_L(0); PG8_BAR; PG8_MMA(0, 0, At, B0); PG8_MMA(0, 1, At, B1); PG8_BAR; PG8_SCHED;
;             PG8_LDA(At, 0, 1); PG8_STAGE(PG8_SB(0, 0), b2, voffB); PG8_STAGE(PG8_SB(0, 1), b2 + hstep, voffB); PG8_STAGE(PG8_SA(0, 0), a2, voffA);
.LBB0_265:
	s_ashr_i32 s17, s16, 31
	s_lshl_b64 s[18:19], s[16:17], 20
	s_add_u32 s18, s90, s18
	s_addc_u32 s19, s91, s19
	s_and_b64 s[20:21], s[6:7], exec
	s_cselect_b32 s17, s19, s29
	s_cselect_b32 s75, s18, s28
	s_ashr_i32 s15, s14, 31
	s_lshl_b64 s[20:21], s[14:15], 20
	s_add_u32 s20, s5, s20
	s_addc_u32 s21, s30, s21
	s_and_b64 s[22:23], s[6:7], exec
	s_cselect_b32 s15, s21, s27
	s_cselect_b32 s85, s20, s26
	s_lshl_b32 s22, s24, 8
	s_ashr_i32 s23, s22, 31
	v_lshl_add_u64 v[128:129], s[22:23], 2, v[154:155]
	s_ashr_i32 s23, s24, 31
	s_lshl_b32 s50, s74, 8
	s_lshr_b32 s23, s23, 27
	s_ashr_i32 s51, s50, 31
	s_add_i32 s23, s24, s23
	v_lshl_add_u64 v[4:5], s[50:51], 2, v[152:153]
	s_ashr_i32 s23, s23, 5
	v_mad_i64_i32 v[132:133], s[24:25], s23, v235, v[4:5]
	s_add_u32 s24, s28, 0x80080
	s_addc_u32 s25, s29, 0
	s_add_u32 s23, s26, 0x100
	v_lshl_add_u64 v[130:131], v[128:129], 0, s[56:57]
	s_addc_u32 s50, s27, 0
	s_mov_b32 s51, -2
	s_mov_b64 s[26:27], 0
.Lup_peel:
	s_add_u32 s28, s24, 0xfff80080
	s_addc_u32 s29, s25, -1
	s_and_b64 s[26:27], s[26:27], exec
	s_cselect_b32 s29, s17, s29
	s_cselect_b32 s28, s75, s28
	s_cselect_b32 s27, s15, s50
	s_cselect_b32 s26, s85, s23
	s_add_i32 s42, 0, 0x10000
	v_add_u32_e32 v134, s42, v161
	s_add_i32 s43, 0, 0x14000
	ds_read_b128 v[140:143], v134
	ds_read_b128 v[144:147], v134 offset:1024
	ds_read_b128 v[166:169], v134 offset:2048
	ds_read_b128 v[170:173], v134 offset:3072
	v_add_u32_e32 v134, s43, v161
	ds_read_b128 v[174:177], v134
	ds_read_b128 v[186:189], v134 offset:1024
	ds_read_b128 v[190:193], v134 offset:2048
	ds_read_b128 v[194:197], v134 offset:3072
	v_lshl_add_u64 v[134:135], s[24:25], 0, v[156:157]
	s_add_i32 m0, s37, 0xc000
	ds_read_b128 v[198:201], v165
	ds_read_b128 v[202:205], v165 offset:1024
	ds_read_b128 v[206:209], v165 offset:2048
	ds_read_b128 v[210:213], v165 offset:3072
	ds_read_b128 v[214:217], v165 offset:4096
	ds_read_b128 v[218:221], v165 offset:5120
	ds_read_b128 v[222:225], v165 offset:6144
	ds_read_b128 v[226:229], v165 offset:7168
	global_load_lds_dwordx4 v[134:135], off
	v_lshl_add_u64 v[134:135], s[24:25], 0, v[158:159]
	s_add_i32 m0, s37, 0xe000
	s_nop 0
	global_load_lds_dwordx4 v[134:135], off
	s_waitcnt vmcnt(8)
	s_waitcnt lgkmcnt(0)
	s_setprio 1
	s_barrier
	v_mfma_f32_16x16x32_bf16 v[134:137], v[140:143], v[198:201], 0
	v_mfma_f32_16x16x32_bf16 v[124:127], v[166:169], v[198:201], 0
	v_mfma_f32_16x16x32_bf16 v[112:115], v[140:143], v[206:209], 0
	v_mfma_f32_16x16x32_bf16 v[108:111], v[166:169], v[206:209], 0
	v_mfma_f32_16x16x32_bf16 v[96:99], v[140:143], v[214:217], 0
	v_mfma_f32_16x16x32_bf16 v[92:95], v[166:169], v[214:217], 0
	v_mfma_f32_16x16x32_bf16 v[80:83], v[140:143], v[222:225], 0
	v_mfma_f32_16x16x32_bf16 v[76:79], v[166:169], v[222:225], 0
	v_mfma_f32_16x16x32_bf16 v[134:137], v[144:147], v[202:205], v[134:137]
	v_mfma_f32_16x16x32_bf16 v[124:127], v[170:173], v[202:205], v[124:127]
	v_mfma_f32_16x16x32_bf16 v[112:115], v[144:147], v[210:213], v[112:115]
	v_mfma_f32_16x16x32_bf16 v[108:111], v[170:173], v[210:213], v[108:111]
	v_mfma_f32_16x16x32_bf16 v[96:99], v[144:147], v[218:221], v[96:99]
	v_mfma_f32_16x16x32_bf16 v[92:95], v[170:173], v[218:221], v[92:95]
	v_mfma_f32_16x16x32_bf16 v[80:83], v[144:147], v[226:229], v[80:83]
	v_mfma_f32_16x16x32_bf16 v[76:79], v[170:173], v[226:229], v[76:79]
	s_setprio 0
	s_setprio 1
	v_mfma_f32_16x16x32_bf16 v[120:123], v[174:177], v[198:201], 0
	v_mfma_f32_16x16x32_bf16 v[116:119], v[190:193], v[198:201], 0
	v_mfma_f32_16x16x32_bf16 v[104:107], v[174:177], v[206:209], 0
	v_mfma_f32_16x16x32_bf16 v[100:103], v[190:193], v[206:209], 0
	v_mfma_f32_16x16x32_bf16 v[88:91], v[174:177], v[214:217], 0
	v_mfma_f32_16x16x32_bf16 v[84:87], v[190:193], v[214:217], 0
	v_mfma_f32_16x16x32_bf16 v[72:75], v[174:177], v[222:225], 0
	v_mfma_f32_16x16x32_bf16 v[68:71], v[190:193], v[222:225], 0
	v_mfma_f32_16x16x32_bf16 v[120:123], v[186:189], v[202:205], v[120:123]
	v_mfma_f32_16x16x32_bf16 v[116:119], v[194:197], v[202:205], v[116:119]
	v_mfma_f32_16x16x32_bf16 v[104:107], v[186:189], v[210:213], v[104:107]
	v_mfma_f32_16x16x32_bf16 v[100:103], v[194:197], v[210:213], v[100:103]
	v_mfma_f32_16x16x32_bf16 v[88:91], v[186:189], v[218:221], v[88:91]
	v_mfma_f32_16x16x32_bf16 v[84:87], v[194:197], v[218:221], v[84:87]
	v_mfma_f32_16x16x32_bf16 v[72:75], v[186:189], v[226:229], v[72:75]
	v_mfma_f32_16x16x32_bf16 v[68:71], v[194:197], v[226:229], v[68:71]
	s_setprio 0
	s_barrier
	s_add_i32 s42, s42, s31
	v_lshl_add_u64 v[178:179], s[26:27], 0, v[2:3]
	s_mov_b32 m0, s42
	ds_read_b128 v[198:201], v165 offset:16384
	ds_read_b128 v[202:205], v165 offset:17408
	ds_read_b128 v[206:209], v165 offset:18432
	ds_read_b128 v[210:213], v165 offset:19456
	ds_read_b128 v[214:217], v165 offset:20480
	ds_read_b128 v[218:221], v165 offset:21504
	ds_read_b128 v[222:225], v165 offset:22528
	ds_read_b128 v[226:229], v165 offset:23552
	global_load_lds_dwordx4 v[178:179], off
	s_add_i32 m0, s42, 0x2000
	s_add_u32 s94, s26, 0x80000
	v_lshl_add_u64 v[180:181], s[26:27], 0, v[0:1]
	s_addc_u32 s95, s27, 0
	s_add_i32 s42, s43, s31
	global_load_lds_dwordx4 v[180:181], off
	v_lshl_add_u64 v[138:139], s[94:95], 0, v[2:3]
	s_mov_b32 m0, s42
	v_lshl_add_u64 v[182:183], s[28:29], 0, v[150:151]
	global_load_lds_dwordx4 v[138:139], off
	v_lshl_add_u64 v[138:139], s[94:95], 0, v[0:1]
	s_add_i32 m0, s42, 0x2000
	v_lshl_add_u64 v[230:231], s[28:29], 0, v[148:149]
	global_load_lds_dwordx4 v[138:139], off
	s_mov_b32 m0, s37
	s_nop 0
	global_load_lds_dwordx4 v[182:183], off
	s_mov_b32 m0, s39
	s_nop 0
	global_load_lds_dwordx4 v[230:231], off
	s_waitcnt vmcnt(8)
	s_waitcnt lgkmcnt(0)
	s_setprio 1
	s_barrier
; #define PG8_STAGE(bufoff, gbase, voff) do { _Pragma("unroll") for (int _i = 0; _i < 2; ++_i) \
;         __builtin_amdgcn_global_load_lds((const unsigned*)((const char*)(gbase) + (voff)[_i]), (PG8_LAS unsigned*)(lds + (bufoff) + ldsw + _i * 8192), 16, 0, 0); } while (0)
; #define PG8_LDA(dst, b, h) do { _Pragma("unroll") for (int m = 0; m < 4; ++m) _Pragma("unroll") for (int k = 0; k < 2; ++k) dst[m][k] = *(const PG8_LAS bf16x8*)(lds + PG8_SA(b, h) + aoff + m * 2048 + k * 1024); } while (0)
; #define PG8_LDB(dst, b, h) do { _Pragma("unroll") for (int n = 0; n < 2; ++n) _Pragma("unroll") for (int k = 0; k < 2; ++k) dst[n][k] = *(const PG8_LAS bf16x8*)(lds + PG8_SB(b, h) + boff + n * 2048 + k * 1024); } while (0)
; #define PG8_MMA(ai, bj, At, Bt) do { __builtin_amdgcn_s_setprio(1); _Pragma("unroll") for (int m = 0; m < 4; ++m) _Pragma("unroll") for (int n = 0; n < 2; ++n) _Pragma("unroll") for (int k = 0; k < 2; ++k) \
;         acc[ai][bj][m][n] = __builtin_amdgcn_mfma_f32_16x16x32_bf16(Bt[n][k], At[m][k], acc[ai][bj][m][n], 0, 0, 0); __builtin_amdgcn_s_setprio(0); } while (0)
; #define PG8_WAIT_V(n) asm volatile("s_waitcnt vmcnt(" #n ")" ::: "memory")
; #define PG8_WAIT_L(n) asm volatile("s_waitcnt lgkmcnt(" #n ")" ::: "memory")
; #define PG8_BAR __builtin_amdgcn_s_barrier()
; #define PG8_SCHED __builtin_amdgcn_sched_barrier(0)
; template <class Epi, class Sched, bool ALIGN_EPI = false, bool SP2 = false>
; __device__ __forceinline__ void gemm_phase(PG8_LAS unsigned char* lds, const Gemm g, const Sched& S, const Epi& E, const int tid) {
;     ...
;             PG8_WAIT_V(8); PG8_WAIT_L(0); PG8_BAR; PG8_MMA(1, 0, At, B0); PG8_MMA(1, 1, At, B1); PG8_BAR; PG8_SCHED;
;             PG8_LDB(B0, 1, 0); PG8_LDB(B1, 1, 1); PG8_SCHED; PG8_LDA(At, 1, 0); PG8_STAGE(PG8_SA(0, 1), a2 + hstep, voffA);
;             PG8_WAIT_V(8); PG8_WAIT_L(0); PG8_BAR; PG8_MMA(0, 0, At, B0); PG8_MMA(0, 1, At, B1); PG8_BAR; PG8_SCHED;
	v_mfma_f32_16x16x32_bf16 v[64:67], v[140:143], v[198:201], 0
	v_mfma_f32_16x16x32_bf16 v[60:63], v[166:169], v[198:201], 0
	v_mfma_f32_16x16x32_bf16 v[48:51], v[140:143], v[206:209], 0
	v_mfma_f32_16x16x32_bf16 v[44:47], v[166:169], v[206:209], 0
	v_mfma_f32_16x16x32_bf16 v[32:35], v[140:143], v[214:217], 0
	v_mfma_f32_16x16x32_bf16 v[28:31], v[166:169], v[214:217], 0
	v_mfma_f32_16x16x32_bf16 v[16:19], v[140:143], v[222:225], 0
	v_mfma_f32_16x16x32_bf16 v[12:15], v[166:169], v[222:225], 0
	v_mfma_f32_16x16x32_bf16 v[64:67], v[144:147], v[202:205], v[64:67]
	v_mfma_f32_16x16x32_bf16 v[60:63], v[170:173], v[202:205], v[60:63]
	v_mfma_f32_16x16x32_bf16 v[48:51], v[144:147], v[210:213], v[48:51]
	v_mfma_f32_16x16x32_bf16 v[44:47], v[170:173], v[210:213], v[44:47]
	v_mfma_f32_16x16x32_bf16 v[32:35], v[144:147], v[218:221], v[32:35]
	v_mfma_f32_16x16x32_bf16 v[28:31], v[170:173], v[218:221], v[28:31]
	v_mfma_f32_16x16x32_bf16 v[16:19], v[144:147], v[226:229], v[16:19]
	v_mfma_f32_16x16x32_bf16 v[12:15], v[170:173], v[226:229], v[12:15]
	s_setprio 0
	s_setprio 1
	v_mfma_f32_16x16x32_bf16 v[56:59], v[174:177], v[198:201], 0
	v_mfma_f32_16x16x32_bf16 v[52:55], v[190:193], v[198:201], 0
	v_mfma_f32_16x16x32_bf16 v[40:43], v[174:177], v[206:209], 0
	v_mfma_f32_16x16x32_bf16 v[36:39], v[190:193], v[206:209], 0
	v_mfma_f32_16x16x32_bf16 v[24:27], v[174:177], v[214:217], 0
	v_mfma_f32_16x16x32_bf16 v[20:23], v[190:193], v[214:217], 0
	v_mfma_f32_16x16x32_bf16 v[8:11], v[174:177], v[222:225], 0
	v_mfma_f32_16x16x32_bf16 v[4:7], v[190:193], v[222:225], 0
	v_mfma_f32_16x16x32_bf16 v[56:59], v[186:189], v[202:205], v[56:59]
	v_mfma_f32_16x16x32_bf16 v[52:55], v[194:197], v[202:205], v[52:55]
	v_mfma_f32_16x16x32_bf16 v[40:43], v[186:189], v[210:213], v[40:43]
	v_mfma_f32_16x16x32_bf16 v[36:39], v[194:197], v[210:213], v[36:39]
	v_mfma_f32_16x16x32_bf16 v[24:27], v[186:189], v[218:221], v[24:27]
	v_mfma_f32_16x16x32_bf16 v[20:23], v[194:197], v[218:221], v[20:23]
	v_mfma_f32_16x16x32_bf16 v[8:11], v[186:189], v[226:229], v[8:11]
	v_mfma_f32_16x16x32_bf16 v[4:7], v[194:197], v[226:229], v[4:7]
	s_setprio 0
	s_barrier
	s_add_i32 s42, 0, 0x18000
	v_add_u32_e32 v138, s42, v161
	s_add_i32 s43, 0, 0x1c000
	ds_read_b128 v[140:143], v138
	ds_read_b128 v[144:147], v138 offset:1024
	ds_read_b128 v[166:169], v138 offset:2048
	ds_read_b128 v[170:173], v138 offset:3072
	v_add_u32_e32 v138, s43, v161
	ds_read_b128 v[174:177], v138
	ds_read_b128 v[186:189], v138 offset:1024
	ds_read_b128 v[190:193], v138 offset:2048
	ds_read_b128 v[194:197], v138 offset:3072
	s_add_u32 s28, s28, 0x80000
	s_addc_u32 s29, s29, 0
	s_mov_b32 m0, s44
	v_lshl_add_u64 v[138:139], s[28:29], 0, v[150:151]
	ds_read_b128 v[198:201], v165 offset:32768
	ds_read_b128 v[202:205], v165 offset:33792
	ds_read_b128 v[206:209], v165 offset:34816
	ds_read_b128 v[210:213], v165 offset:35840
	ds_read_b128 v[214:217], v165 offset:36864
	ds_read_b128 v[218:221], v165 offset:37888
	ds_read_b128 v[222:225], v165 offset:38912
	ds_read_b128 v[226:229], v165 offset:39936
	global_load_lds_dwordx4 v[138:139], off
	v_lshl_add_u64 v[138:139], s[28:29], 0, v[148:149]
	s_mov_b32 m0, s48
	s_nop 0
	global_load_lds_dwordx4 v[138:139], off
	s_waitcnt vmcnt(8)
	s_waitcnt lgkmcnt(0)
	s_setprio 1
	s_barrier
	v_mfma_f32_16x16x32_bf16 v[134:137], v[140:143], v[198:201], v[134:137]
	v_mfma_f32_16x16x32_bf16 v[124:127], v[166:169], v[198:201], v[124:127]
	v_mfma_f32_16x16x32_bf16 v[112:115], v[140:143], v[206:209], v[112:115]
	v_mfma_f32_16x16x32_bf16 v[108:111], v[166:169], v[206:209], v[108:111]
	v_mfma_f32_16x16x32_bf16 v[96:99], v[140:143], v[214:217], v[96:99]
	v_mfma_f32_16x16x32_bf16 v[92:95], v[166:169], v[214:217], v[92:95]
	v_mfma_f32_16x16x32_bf16 v[80:83], v[140:143], v[222:225], v[80:83]
	v_mfma_f32_16x16x32_bf16 v[76:79], v[166:169], v[222:225], v[76:79]
	v_mfma_f32_16x16x32_bf16 v[136:139], v[144:147], v[202:205], v[134:137]
	v_mfma_f32_16x16x32_bf16 v[124:127], v[170:173], v[202:205], v[124:127]
	v_mfma_f32_16x16x32_bf16 v[112:115], v[144:147], v[210:213], v[112:115]
	v_mfma_f32_16x16x32_bf16 v[108:111], v[170:173], v[210:213], v[108:111]
	v_mfma_f32_16x16x32_bf16 v[96:99], v[144:147], v[218:221], v[96:99]
	v_mfma_f32_16x16x32_bf16 v[92:95], v[170:173], v[218:221], v[92:95]
	v_mfma_f32_16x16x32_bf16 v[80:83], v[144:147], v[226:229], v[80:83]
	v_mfma_f32_16x16x32_bf16 v[76:79], v[170:173], v[226:229], v[76:79]
	s_setprio 0
	s_setprio 1
	v_mfma_f32_16x16x32_bf16 v[120:123], v[174:177], v[198:201], v[120:123]
	v_mfma_f32_16x16x32_bf16 v[116:119], v[190:193], v[198:201], v[116:119]
	v_mfma_f32_16x16x32_bf16 v[104:107], v[174:177], v[206:209], v[104:107]
	v_mfma_f32_16x16x32_bf16 v[100:103], v[190:193], v[206:209], v[100:103]
	v_mfma_f32_16x16x32_bf16 v[88:91], v[174:177], v[214:217], v[88:91]
	v_mfma_f32_16x16x32_bf16 v[84:87], v[190:193], v[214:217], v[84:87]
	v_mfma_f32_16x16x32_bf16 v[72:75], v[174:177], v[222:225], v[72:75]
	v_mfma_f32_16x16x32_bf16 v[68:71], v[190:193], v[222:225], v[68:71]
	v_mfma_f32_16x16x32_bf16 v[120:123], v[186:189], v[202:205], v[120:123]
	v_mfma_f32_16x16x32_bf16 v[116:119], v[194:197], v[202:205], v[116:119]
	v_mfma_f32_16x16x32_bf16 v[104:107], v[186:189], v[210:213], v[104:107]
	v_mfma_f32_16x16x32_bf16 v[100:103], v[194:197], v[210:213], v[100:103]
	v_mfma_f32_16x16x32_bf16 v[88:91], v[186:189], v[218:221], v[88:91]
	v_mfma_f32_16x16x32_bf16 v[84:87], v[194:197], v[218:221], v[84:87]
	v_mfma_f32_16x16x32_bf16 v[72:75], v[186:189], v[226:229], v[72:75]
	v_mfma_f32_16x16x32_bf16 v[68:71], v[194:197], v[226:229], v[68:71]
	s_setprio 0
	s_barrier
; #define PG8_STAGE(bufoff, gbase, voff) do { _Pragma("unroll") for (int _i = 0; _i < 2; ++_i) \
;         __builtin_amdgcn_global_load_lds((const unsigned*)((const char*)(gbase) + (voff)[_i]), (PG8_LAS unsigned*)(lds + (bufoff) + ldsw + _i * 8192), 16, 0, 0); } while (0)
; #define PG8_LDA(dst, b, h) do { _Pragma("unroll") for (int m = 0; m < 4; ++m) _Pragma("unroll") for (int k = 0; k < 2; ++k) dst[m][k] = *(const PG8_LAS bf16x8*)(lds + PG8_SA(b, h) + aoff + m * 2048 + k * 1024); } while (0)
; #define PG8_WAIT_V(n) asm volatile("s_waitcnt vmcnt(" #n ")" ::: "memory")
; #define PG8_BAR __builtin_amdgcn_s_barrier()
; template <class Epi, class Sched, bool ALIGN_EPI = false, bool SP2 = false>
; __device__ __forceinline__ void gemm_phase(PG8_LAS unsigned char* lds, const Gemm g, const Sched& S, const Epi& E, const int tid) {
;     ...
;         for (int t = 0; t < nt; t += 2) {
;             const bool last = (t == nt - 2);
;             const char* a1 = cA + (size_t)(t + 1) * kstep;
;             const char* a2 = last ? nA : cA + (size_t)(t + 2) * kstep; const char* b2 = last ? nB : cB + (size_t)(t + 2) * kstep;
;             const char* a3 = a2 + kstep; const char* b3 = b2 + kstep;
;             if (last && has_next) S.a_ready(nxt);
;             if (last) E.prefetch(lds + EPI_LDS_OFF + wid * 1024, cur, wr, wc, lane);
;             if constexpr (SP2) {
;             PG8_LDB(B0, 0, 0); PG8_LDB(B1, 0, 1); PG8_SCHED; PG8_LDA(At, 0, 0); PG8_STAGE(PG8_SA(1, 1), a1 + hstep, voffA);
;             PG8_WAIT_V(8); PG8_WAIT_L(0); PG8_BAR; PG8_MMA(0, 0, At, B0); PG8_MMA(0, 1, At, B1); PG8_BAR; PG8_SCHED;
;             PG8_LDA(At, 0, 1); PG8_STAGE(PG8_SB(0, 0), b2, voffB); PG8_STAGE(PG8_SB(0, 1), b2 + hstep, voffB); PG8_STAGE(PG8_SA(0, 0), a2, voffA);
;             PG8_WAIT_V(8); PG8_WAIT_L(0); PG8_BAR; PG8_MMA(1, 0, At, B0); PG8_MMA(1, 1, At, B1); PG8_BAR; PG8_SCHED;
;             PG8_LDB(B0, 1, 0); PG8_LDB(B1, 1, 1); PG8_SCHED; PG8_LDA(At, 1, 0); PG8_STAGE(PG8_SA(0, 1), a2 + hstep, voffA);
;             PG8_WAIT_V(8); PG8_WAIT_L(0); PG8_BAR; PG8_MMA(0, 0, At, B0); PG8_MMA(0, 1, At, B1); PG8_BAR; PG8_SCHED;
;             PG8_LDA(At, 1, 1); PG8_STAGE(PG8_SB(1, 0), b3, voffB); PG8_STAGE(PG8_SB(1, 1), b3 + hstep, voffB); PG8_STAGE(PG8_SA(1, 0), a3, voffA);
;             PG8_WAIT_V(8); PG8_WAIT_L(0); PG8_BAR; PG8_MMA(1, 0, At, B0); PG8_MMA(1, 1, At, B1); PG8_BAR; PG8_SCHED;
	s_add_i32 s28, s42, s31
	v_lshl_add_u64 v[134:135], v[178:179], 0, s[46:47]
	s_mov_b32 m0, s28
	ds_read_b128 v[198:201], v165 offset:49152
	ds_read_b128 v[202:205], v165 offset:50176
	ds_read_b128 v[206:209], v165 offset:51200
	ds_read_b128 v[210:213], v165 offset:52224
	ds_read_b128 v[214:217], v165 offset:53248
	ds_read_b128 v[218:221], v165 offset:54272
	ds_read_b128 v[222:225], v165 offset:55296
	ds_read_b128 v[226:229], v165 offset:56320
	global_load_lds_dwordx4 v[134:135], off
	s_add_i32 m0, s28, 0x2000
	s_add_u32 s26, s26, 0x80080
	v_lshl_add_u64 v[134:135], v[180:181], 0, s[46:47]
	s_addc_u32 s27, s27, 0
	s_add_i32 s28, s43, s31
	global_load_lds_dwordx4 v[134:135], off
	v_lshl_add_u64 v[134:135], s[26:27], 0, v[2:3]
	s_mov_b32 m0, s28
	s_nop 0
	global_load_lds_dwordx4 v[134:135], off
	v_lshl_add_u64 v[134:135], s[26:27], 0, v[0:1]
	s_add_i32 m0, s28, 0x2000
	s_nop 0
	global_load_lds_dwordx4 v[134:135], off
	v_lshl_add_u64 v[134:135], v[182:183], 0, s[46:47]
	s_mov_b32 m0, s52
	s_nop 0
	global_load_lds_dwordx4 v[134:135], off
	v_lshl_add_u64 v[134:135], v[230:231], 0, s[46:47]
	s_mov_b32 m0, s53
	s_nop 0
	global_load_lds_dwordx4 v[134:135], off
	s_waitcnt vmcnt(8)
	s_waitcnt lgkmcnt(0)
	s_setprio 1
	s_barrier
	v_mfma_f32_16x16x32_bf16 v[64:67], v[140:143], v[198:201], v[64:67]
	v_mfma_f32_16x16x32_bf16 v[60:63], v[166:169], v[198:201], v[60:63]
	v_mfma_f32_16x16x32_bf16 v[48:51], v[140:143], v[206:209], v[48:51]
	v_mfma_f32_16x16x32_bf16 v[44:47], v[166:169], v[206:209], v[44:47]
	v_mfma_f32_16x16x32_bf16 v[32:35], v[140:143], v[214:217], v[32:35]
	v_mfma_f32_16x16x32_bf16 v[28:31], v[166:169], v[214:217], v[28:31]
	v_mfma_f32_16x16x32_bf16 v[16:19], v[140:143], v[222:225], v[16:19]
	v_mfma_f32_16x16x32_bf16 v[12:15], v[166:169], v[222:225], v[12:15]
	v_mfma_f32_16x16x32_bf16 v[64:67], v[144:147], v[202:205], v[64:67]
	v_mfma_f32_16x16x32_bf16 v[60:63], v[170:173], v[202:205], v[60:63]
	v_mfma_f32_16x16x32_bf16 v[48:51], v[144:147], v[210:213], v[48:51]
	v_mfma_f32_16x16x32_bf16 v[44:47], v[170:173], v[210:213], v[44:47]
	v_mfma_f32_16x16x32_bf16 v[32:35], v[144:147], v[218:221], v[32:35]
	v_mfma_f32_16x16x32_bf16 v[28:31], v[170:173], v[218:221], v[28:31]
	v_mfma_f32_16x16x32_bf16 v[16:19], v[144:147], v[226:229], v[16:19]
	v_mfma_f32_16x16x32_bf16 v[12:15], v[170:173], v[226:229], v[12:15]
	s_setprio 0
	s_setprio 1
	v_mfma_f32_16x16x32_bf16 v[56:59], v[174:177], v[198:201], v[56:59]
	v_mfma_f32_16x16x32_bf16 v[52:55], v[190:193], v[198:201], v[52:55]
	v_mfma_f32_16x16x32_bf16 v[40:43], v[174:177], v[206:209], v[40:43]
	v_mfma_f32_16x16x32_bf16 v[36:39], v[190:193], v[206:209], v[36:39]
	v_mfma_f32_16x16x32_bf16 v[24:27], v[174:177], v[214:217], v[24:27]
	v_mfma_f32_16x16x32_bf16 v[20:23], v[190:193], v[214:217], v[20:23]
	v_mfma_f32_16x16x32_bf16 v[8:11], v[174:177], v[222:225], v[8:11]
	v_mfma_f32_16x16x32_bf16 v[4:7], v[190:193], v[222:225], v[4:7]
	v_mfma_f32_16x16x32_bf16 v[56:59], v[186:189], v[202:205], v[56:59]
	v_mfma_f32_16x16x32_bf16 v[52:55], v[194:197], v[202:205], v[52:55]
	v_mfma_f32_16x16x32_bf16 v[40:43], v[186:189], v[210:213], v[40:43]
	v_mfma_f32_16x16x32_bf16 v[36:39], v[194:197], v[210:213], v[36:39]
	v_mfma_f32_16x16x32_bf16 v[24:27], v[186:189], v[218:221], v[24:27]
	v_mfma_f32_16x16x32_bf16 v[20:23], v[194:197], v[218:221], v[20:23]
	v_mfma_f32_16x16x32_bf16 v[8:11], v[186:189], v[226:229], v[8:11]
	v_mfma_f32_16x16x32_bf16 v[4:7], v[194:197], v[226:229], v[4:7]
	s_setprio 0
	s_barrier
	s_add_i32 s51, s51, 2
	s_add_u32 s24, s24, 0x100
	s_addc_u32 s25, s25, 0
	s_add_u32 s23, s23, 0x100
	s_addc_u32 s50, s50, 0
	s_cmp_gt_u32 s51, 29
	s_cbranch_scc1 .LBB0_269
	s_branch .LBB0_267
